# out-projection K-loop: last iteration peeled, no prefetch of K-tiles beyond the unit (the drain before the epilogue no longer waits for unused loads)
# baseline (speedup 1.0000x reference)
.LBB0_920:
	ds_read_b128 v[148:151], v142 offset:3072
	ds_read_b128 v[152:155], v142 offset:2048
	ds_read_b128 v[156:159], v142 offset:1024
	ds_read_b128 v[160:163], v142
	ds_read_b128 v[166:169], v143 offset:3072
	ds_read_b128 v[170:173], v143 offset:2048
	ds_read_b128 v[174:177], v143 offset:1024
	ds_read_b128 v[178:181], v143
	s_add_u32 s12, s82, s27
	s_addc_u32 s13, s83, s28
	s_add_u32 s14, s82, s25
	s_addc_u32 s15, s83, s26
	s_cmp_eq_u32 s29, 12
	s_cselect_b32 s16, s0, s12
	s_cselect_b32 s17, s1, s13
	s_cselect_b32 s15, s3, s15
	s_cselect_b32 s14, s2, s14
	s_add_u32 s12, s16, 0x200000
	s_addc_u32 s13, s17, 0
	s_mov_b32 m0, s30
	v_lshl_add_u64 v[214:215], s[82:83], 0, v[138:139]
	ds_read_b128 v[182:185], v144
	ds_read_b128 v[186:189], v144 offset:1024
	ds_read_b128 v[190:193], v144 offset:2048
	ds_read_b128 v[194:197], v144 offset:3072
	ds_read_b128 v[198:201], v144 offset:4096
	ds_read_b128 v[202:205], v144 offset:5120
	ds_read_b128 v[206:209], v144 offset:6144
	ds_read_b128 v[210:213], v144 offset:7168
	global_load_lds_dwordx4 v[214:215], off
	v_lshl_add_u64 v[214:215], s[82:83], 0, v[140:141]
	s_mov_b32 m0, s31
	s_nop 0
	global_load_lds_dwordx4 v[214:215], off
	s_waitcnt vmcnt(8)
	s_waitcnt lgkmcnt(0)
	s_barrier
	s_setprio 1
	s_waitcnt lgkmcnt(0)
	v_mfma_f32_16x16x32_bf16 v[66:69], v[178:181], v[182:185], v[66:69]
	v_mfma_f32_16x16x32_bf16 v[38:41], v[170:173], v[182:185], v[38:41]
	v_mfma_f32_16x16x32_bf16 v[78:81], v[178:181], v[190:193], v[78:81]
	v_mfma_f32_16x16x32_bf16 v[46:49], v[170:173], v[190:193], v[46:49]
	v_mfma_f32_16x16x32_bf16 v[90:93], v[178:181], v[198:201], v[90:93]
	v_mfma_f32_16x16x32_bf16 v[58:61], v[170:173], v[198:201], v[58:61]
	v_mfma_f32_16x16x32_bf16 v[102:105], v[178:181], v[206:209], v[102:105]
	v_mfma_f32_16x16x32_bf16 v[70:73], v[170:173], v[206:209], v[70:73]
	v_mfma_f32_16x16x32_bf16 v[66:69], v[174:177], v[186:189], v[66:69]
	v_mfma_f32_16x16x32_bf16 v[38:41], v[166:169], v[186:189], v[38:41]
	v_mfma_f32_16x16x32_bf16 v[78:81], v[174:177], v[194:197], v[78:81]
	v_mfma_f32_16x16x32_bf16 v[46:49], v[166:169], v[194:197], v[46:49]
	v_mfma_f32_16x16x32_bf16 v[90:93], v[174:177], v[202:205], v[90:93]
	v_mfma_f32_16x16x32_bf16 v[58:61], v[166:169], v[202:205], v[58:61]
	v_mfma_f32_16x16x32_bf16 v[102:105], v[174:177], v[210:213], v[102:105]
	v_mfma_f32_16x16x32_bf16 v[70:73], v[166:169], v[210:213], v[70:73]
	s_setprio 0
	s_setprio 1
	v_mfma_f32_16x16x32_bf16 v[14:17], v[160:163], v[182:185], v[14:17]
	v_mfma_f32_16x16x32_bf16 v[2:5], v[152:155], v[182:185], v[2:5]
	v_mfma_f32_16x16x32_bf16 v[22:25], v[160:163], v[190:193], v[22:25]
	v_mfma_f32_16x16x32_bf16 v[6:9], v[152:155], v[190:193], v[6:9]
	v_mfma_f32_16x16x32_bf16 v[30:33], v[160:163], v[198:201], v[30:33]
	v_mfma_f32_16x16x32_bf16 v[10:13], v[152:155], v[198:201], v[10:13]
	v_mfma_f32_16x16x32_bf16 v[42:45], v[160:163], v[206:209], v[42:45]
	v_mfma_f32_16x16x32_bf16 v[18:21], v[152:155], v[206:209], v[18:21]
	v_mfma_f32_16x16x32_bf16 v[14:17], v[156:159], v[186:189], v[14:17]
	v_mfma_f32_16x16x32_bf16 v[2:5], v[148:151], v[186:189], v[2:5]
	v_mfma_f32_16x16x32_bf16 v[22:25], v[156:159], v[194:197], v[22:25]
	v_mfma_f32_16x16x32_bf16 v[6:9], v[148:151], v[194:197], v[6:9]
	v_mfma_f32_16x16x32_bf16 v[30:33], v[156:159], v[202:205], v[30:33]
	v_mfma_f32_16x16x32_bf16 v[10:13], v[148:151], v[202:205], v[10:13]
	v_mfma_f32_16x16x32_bf16 v[42:45], v[156:159], v[210:213], v[42:45]
	v_mfma_f32_16x16x32_bf16 v[18:21], v[148:151], v[210:213], v[18:21]
	s_setprio 0
	s_barrier
	s_mov_b32 m0, s33
	v_lshl_add_u64 v[214:215], s[14:15], 0, v[132:133]
	s_add_u32 s42, s14, 0x40000
	ds_read_b128 v[182:185], v144 offset:16384
	ds_read_b128 v[186:189], v144 offset:17408
	ds_read_b128 v[190:193], v144 offset:18432
	ds_read_b128 v[194:197], v144 offset:19456
	ds_read_b128 v[198:201], v144 offset:20480
	ds_read_b128 v[202:205], v144 offset:21504
	ds_read_b128 v[206:209], v144 offset:22528
	ds_read_b128 v[210:213], v144 offset:23552
	global_load_lds_dwordx4 v[214:215], off
	v_lshl_add_u64 v[216:217], s[14:15], 0, v[136:137]
	s_mov_b32 m0, s34
	s_addc_u32 s43, s15, 0
	global_load_lds_dwordx4 v[216:217], off
	v_lshl_add_u64 v[218:219], s[42:43], 0, v[132:133]
	s_mov_b32 m0, s35
	s_nop 0
	global_load_lds_dwordx4 v[218:219], off
	v_lshl_add_u64 v[218:219], s[42:43], 0, v[136:137]
	s_mov_b32 m0, s36
	s_nop 0
	global_load_lds_dwordx4 v[218:219], off
	v_lshl_add_u64 v[218:219], s[16:17], 0, v[130:131]
	s_mov_b32 m0, s7
	s_nop 0
	global_load_lds_dwordx4 v[218:219], off
	v_lshl_add_u64 v[218:219], s[16:17], 0, v[134:135]
	s_mov_b32 m0, s20
	s_nop 0
	global_load_lds_dwordx4 v[218:219], off
	s_waitcnt vmcnt(8)
	s_waitcnt lgkmcnt(0)
	s_barrier
	s_setprio 1
	s_waitcnt lgkmcnt(0)
	v_mfma_f32_16x16x32_bf16 v[106:109], v[178:181], v[182:185], v[106:109]
	v_mfma_f32_16x16x32_bf16 v[82:85], v[170:173], v[182:185], v[82:85]
	v_mfma_f32_16x16x32_bf16 v[118:121], v[178:181], v[190:193], v[118:121]
	v_mfma_f32_16x16x32_bf16 v[94:97], v[170:173], v[190:193], v[94:97]
	v_mfma_f32_16x16x32_bf16 v[126:129], v[178:181], v[198:201], v[126:129]
	v_mfma_f32_16x16x32_bf16 v[110:113], v[170:173], v[198:201], v[110:113]
	v_mfma_f32_16x16x32_bf16 v[122:125], v[178:181], v[206:209], v[122:125]
	v_mfma_f32_16x16x32_bf16 v[114:117], v[170:173], v[206:209], v[114:117]
	v_mfma_f32_16x16x32_bf16 v[106:109], v[174:177], v[186:189], v[106:109]
	v_mfma_f32_16x16x32_bf16 v[82:85], v[166:169], v[186:189], v[82:85]
	v_mfma_f32_16x16x32_bf16 v[118:121], v[174:177], v[194:197], v[118:121]
	v_mfma_f32_16x16x32_bf16 v[94:97], v[166:169], v[194:197], v[94:97]
	v_mfma_f32_16x16x32_bf16 v[126:129], v[174:177], v[202:205], v[126:129]
	v_mfma_f32_16x16x32_bf16 v[110:113], v[166:169], v[202:205], v[110:113]
	v_mfma_f32_16x16x32_bf16 v[122:125], v[174:177], v[210:213], v[122:125]
	v_mfma_f32_16x16x32_bf16 v[114:117], v[166:169], v[210:213], v[114:117]
	s_setprio 0
	s_setprio 1
	v_mfma_f32_16x16x32_bf16 v[50:53], v[160:163], v[182:185], v[50:53]
	v_mfma_f32_16x16x32_bf16 v[26:29], v[152:155], v[182:185], v[26:29]
	v_mfma_f32_16x16x32_bf16 v[62:65], v[160:163], v[190:193], v[62:65]
	v_mfma_f32_16x16x32_bf16 v[34:37], v[152:155], v[190:193], v[34:37]
	v_mfma_f32_16x16x32_bf16 v[86:89], v[160:163], v[198:201], v[86:89]
	v_mfma_f32_16x16x32_bf16 v[54:57], v[152:155], v[198:201], v[54:57]
	v_mfma_f32_16x16x32_bf16 v[98:101], v[160:163], v[206:209], v[98:101]
	v_mfma_f32_16x16x32_bf16 v[74:77], v[152:155], v[206:209], v[74:77]
	v_mfma_f32_16x16x32_bf16 v[50:53], v[156:159], v[186:189], v[50:53]
	v_mfma_f32_16x16x32_bf16 v[26:29], v[148:151], v[186:189], v[26:29]
	v_mfma_f32_16x16x32_bf16 v[62:65], v[156:159], v[194:197], v[62:65]
	v_mfma_f32_16x16x32_bf16 v[34:37], v[148:151], v[194:197], v[34:37]
	v_mfma_f32_16x16x32_bf16 v[86:89], v[156:159], v[202:205], v[86:89]
	v_mfma_f32_16x16x32_bf16 v[54:57], v[148:151], v[202:205], v[54:57]
	v_mfma_f32_16x16x32_bf16 v[98:101], v[156:159], v[210:213], v[98:101]
	v_mfma_f32_16x16x32_bf16 v[74:77], v[148:151], v[210:213], v[74:77]
	s_setprio 0
	s_barrier
	ds_read_b128 v[148:151], v145
	ds_read_b128 v[152:155], v145 offset:1024
	ds_read_b128 v[156:159], v145 offset:2048
	ds_read_b128 v[160:163], v145 offset:3072
	ds_read_b128 v[166:169], v146
	ds_read_b128 v[170:173], v146 offset:1024
	ds_read_b128 v[174:177], v146 offset:2048
	ds_read_b128 v[178:181], v146 offset:3072
	s_add_u32 s16, s16, 0x4000
	s_addc_u32 s17, s17, 0
	s_mov_b32 m0, s21
	v_lshl_add_u64 v[218:219], s[16:17], 0, v[130:131]
	ds_read_b128 v[182:185], v144 offset:32768
	ds_read_b128 v[186:189], v144 offset:33792
	ds_read_b128 v[190:193], v144 offset:34816
	ds_read_b128 v[194:197], v144 offset:35840
	ds_read_b128 v[198:201], v144 offset:36864
	ds_read_b128 v[202:205], v144 offset:37888
	ds_read_b128 v[206:209], v144 offset:38912
	ds_read_b128 v[210:213], v144 offset:39936
	global_load_lds_dwordx4 v[218:219], off
	v_lshl_add_u64 v[218:219], s[16:17], 0, v[134:135]
	s_mov_b32 m0, s22
	s_nop 0
	global_load_lds_dwordx4 v[218:219], off
	s_waitcnt vmcnt(8)
	s_waitcnt lgkmcnt(0)
	s_barrier
	s_setprio 1
	s_waitcnt lgkmcnt(0)
	v_mfma_f32_16x16x32_bf16 v[66:69], v[148:151], v[182:185], v[66:69]
	v_mfma_f32_16x16x32_bf16 v[38:41], v[156:159], v[182:185], v[38:41]
	v_mfma_f32_16x16x32_bf16 v[78:81], v[148:151], v[190:193], v[78:81]
	v_mfma_f32_16x16x32_bf16 v[46:49], v[156:159], v[190:193], v[46:49]
	v_mfma_f32_16x16x32_bf16 v[90:93], v[148:151], v[198:201], v[90:93]
	v_mfma_f32_16x16x32_bf16 v[58:61], v[156:159], v[198:201], v[58:61]
	v_mfma_f32_16x16x32_bf16 v[102:105], v[148:151], v[206:209], v[102:105]
	v_mfma_f32_16x16x32_bf16 v[70:73], v[156:159], v[206:209], v[70:73]
	v_mfma_f32_16x16x32_bf16 v[66:69], v[152:155], v[186:189], v[66:69]
	v_mfma_f32_16x16x32_bf16 v[38:41], v[160:163], v[186:189], v[38:41]
	v_mfma_f32_16x16x32_bf16 v[78:81], v[152:155], v[194:197], v[78:81]
	v_mfma_f32_16x16x32_bf16 v[46:49], v[160:163], v[194:197], v[46:49]
	v_mfma_f32_16x16x32_bf16 v[90:93], v[152:155], v[202:205], v[90:93]
	v_mfma_f32_16x16x32_bf16 v[58:61], v[160:163], v[202:205], v[58:61]
	v_mfma_f32_16x16x32_bf16 v[102:105], v[152:155], v[210:213], v[102:105]
	v_mfma_f32_16x16x32_bf16 v[70:73], v[160:163], v[210:213], v[70:73]
	s_setprio 0
	s_setprio 1
	v_mfma_f32_16x16x32_bf16 v[14:17], v[166:169], v[182:185], v[14:17]
	v_mfma_f32_16x16x32_bf16 v[2:5], v[174:177], v[182:185], v[2:5]
	v_mfma_f32_16x16x32_bf16 v[22:25], v[166:169], v[190:193], v[22:25]
	v_mfma_f32_16x16x32_bf16 v[6:9], v[174:177], v[190:193], v[6:9]
	v_mfma_f32_16x16x32_bf16 v[30:33], v[166:169], v[198:201], v[30:33]
	v_mfma_f32_16x16x32_bf16 v[10:13], v[174:177], v[198:201], v[10:13]
	v_mfma_f32_16x16x32_bf16 v[42:45], v[166:169], v[206:209], v[42:45]
	v_mfma_f32_16x16x32_bf16 v[18:21], v[174:177], v[206:209], v[18:21]
	v_mfma_f32_16x16x32_bf16 v[14:17], v[170:173], v[186:189], v[14:17]
	v_mfma_f32_16x16x32_bf16 v[2:5], v[178:181], v[186:189], v[2:5]
	v_mfma_f32_16x16x32_bf16 v[22:25], v[170:173], v[194:197], v[22:25]
	v_mfma_f32_16x16x32_bf16 v[6:9], v[178:181], v[194:197], v[6:9]
	v_mfma_f32_16x16x32_bf16 v[30:33], v[170:173], v[202:205], v[30:33]
	v_mfma_f32_16x16x32_bf16 v[10:13], v[178:181], v[202:205], v[10:13]
	v_mfma_f32_16x16x32_bf16 v[42:45], v[170:173], v[210:213], v[42:45]
	v_mfma_f32_16x16x32_bf16 v[18:21], v[178:181], v[210:213], v[18:21]
	s_setprio 0
	s_barrier
	s_mov_b32 m0, s37
	v_lshl_add_u64 v[214:215], v[214:215], 0, s[4:5]
	s_add_u32 s14, s14, 0x40080
	ds_read_b128 v[182:185], v144 offset:49152
	ds_read_b128 v[186:189], v144 offset:50176
	ds_read_b128 v[190:193], v144 offset:51200
	ds_read_b128 v[194:197], v144 offset:52224
	ds_read_b128 v[198:201], v144 offset:53248
	ds_read_b128 v[202:205], v144 offset:54272
	ds_read_b128 v[206:209], v144 offset:55296
	ds_read_b128 v[210:213], v144 offset:56320
	global_load_lds_dwordx4 v[214:215], off
	v_lshl_add_u64 v[214:215], v[216:217], 0, s[4:5]
	s_mov_b32 m0, s38
	s_addc_u32 s15, s15, 0
	global_load_lds_dwordx4 v[214:215], off
	v_lshl_add_u64 v[214:215], s[14:15], 0, v[132:133]
	s_mov_b32 m0, s39
	s_nop 0
	global_load_lds_dwordx4 v[214:215], off
	v_lshl_add_u64 v[214:215], s[14:15], 0, v[136:137]
	s_mov_b32 m0, s40
	s_nop 0
	global_load_lds_dwordx4 v[214:215], off
	v_lshl_add_u64 v[214:215], s[12:13], 0, v[130:131]
	s_mov_b32 m0, s23
	s_nop 0
	global_load_lds_dwordx4 v[214:215], off
	v_lshl_add_u64 v[214:215], s[12:13], 0, v[134:135]
	s_mov_b32 m0, s24
	s_nop 0
	global_load_lds_dwordx4 v[214:215], off
	s_waitcnt vmcnt(8)
	s_waitcnt lgkmcnt(0)
	s_barrier
	s_setprio 1
	s_waitcnt lgkmcnt(0)
	v_mfma_f32_16x16x32_bf16 v[106:109], v[148:151], v[182:185], v[106:109]
	v_mfma_f32_16x16x32_bf16 v[82:85], v[156:159], v[182:185], v[82:85]
	v_mfma_f32_16x16x32_bf16 v[118:121], v[148:151], v[190:193], v[118:121]
	v_mfma_f32_16x16x32_bf16 v[94:97], v[156:159], v[190:193], v[94:97]
	v_mfma_f32_16x16x32_bf16 v[126:129], v[148:151], v[198:201], v[126:129]
	v_mfma_f32_16x16x32_bf16 v[110:113], v[156:159], v[198:201], v[110:113]
	v_mfma_f32_16x16x32_bf16 v[122:125], v[148:151], v[206:209], v[122:125]
	v_mfma_f32_16x16x32_bf16 v[114:117], v[156:159], v[206:209], v[114:117]
	v_mfma_f32_16x16x32_bf16 v[106:109], v[152:155], v[186:189], v[106:109]
	v_mfma_f32_16x16x32_bf16 v[82:85], v[160:163], v[186:189], v[82:85]
	v_mfma_f32_16x16x32_bf16 v[118:121], v[152:155], v[194:197], v[118:121]
	v_mfma_f32_16x16x32_bf16 v[94:97], v[160:163], v[194:197], v[94:97]
	v_mfma_f32_16x16x32_bf16 v[126:129], v[152:155], v[202:205], v[126:129]
	v_mfma_f32_16x16x32_bf16 v[110:113], v[160:163], v[202:205], v[110:113]
	v_mfma_f32_16x16x32_bf16 v[122:125], v[152:155], v[210:213], v[122:125]
	v_mfma_f32_16x16x32_bf16 v[114:117], v[160:163], v[210:213], v[114:117]
	s_setprio 0
	s_setprio 1
	v_mfma_f32_16x16x32_bf16 v[50:53], v[166:169], v[182:185], v[50:53]
	v_mfma_f32_16x16x32_bf16 v[26:29], v[174:177], v[182:185], v[26:29]
	v_mfma_f32_16x16x32_bf16 v[62:65], v[166:169], v[190:193], v[62:65]
	v_mfma_f32_16x16x32_bf16 v[34:37], v[174:177], v[190:193], v[34:37]
	v_mfma_f32_16x16x32_bf16 v[86:89], v[166:169], v[198:201], v[86:89]
	v_mfma_f32_16x16x32_bf16 v[54:57], v[174:177], v[198:201], v[54:57]
	v_mfma_f32_16x16x32_bf16 v[98:101], v[166:169], v[206:209], v[98:101]
	v_mfma_f32_16x16x32_bf16 v[74:77], v[174:177], v[206:209], v[74:77]
	v_mfma_f32_16x16x32_bf16 v[50:53], v[170:173], v[186:189], v[50:53]
	v_mfma_f32_16x16x32_bf16 v[26:29], v[178:181], v[186:189], v[26:29]
	v_mfma_f32_16x16x32_bf16 v[62:65], v[170:173], v[194:197], v[62:65]
	v_mfma_f32_16x16x32_bf16 v[34:37], v[178:181], v[194:197], v[34:37]
	v_mfma_f32_16x16x32_bf16 v[86:89], v[170:173], v[202:205], v[86:89]
	v_mfma_f32_16x16x32_bf16 v[54:57], v[178:181], v[202:205], v[54:57]
	v_mfma_f32_16x16x32_bf16 v[98:101], v[170:173], v[210:213], v[98:101]
	v_mfma_f32_16x16x32_bf16 v[74:77], v[178:181], v[210:213], v[74:77]
	s_setprio 0
	s_barrier
	s_add_i32 s29, s29, 2
	s_add_u32 s25, s25, 0x100
	s_addc_u32 s26, s26, 0
	s_add_u32 s27, s27, 0x400000
	s_addc_u32 s28, s28, 0
	v_lshl_add_u64 v[138:139], v[138:139], 0, s[10:11]
	s_cmp_lt_u32 s29, 12
	v_lshl_add_u64 v[140:141], v[140:141], 0, s[10:11]
	s_cbranch_scc1 .LBB0_920
	ds_read_b128 v[148:151], v142 offset:3072
	ds_read_b128 v[152:155], v142 offset:2048
	ds_read_b128 v[156:159], v142 offset:1024
	ds_read_b128 v[160:163], v142
	ds_read_b128 v[166:169], v143 offset:3072
	ds_read_b128 v[170:173], v143 offset:2048
	ds_read_b128 v[174:177], v143 offset:1024
	ds_read_b128 v[178:181], v143
	s_add_u32 s12, s82, s27
	s_addc_u32 s13, s83, s28
	s_add_u32 s14, s82, s25
	s_addc_u32 s15, s83, s26
	s_cmp_eq_u32 s29, 12
	s_cselect_b32 s16, s0, s12
	s_cselect_b32 s17, s1, s13
	s_cselect_b32 s15, s3, s15
	s_cselect_b32 s14, s2, s14
	s_add_u32 s12, s16, 0x200000
	s_addc_u32 s13, s17, 0
	s_mov_b32 m0, s30
	v_lshl_add_u64 v[214:215], s[82:83], 0, v[138:139]
	ds_read_b128 v[182:185], v144
	ds_read_b128 v[186:189], v144 offset:1024
	ds_read_b128 v[190:193], v144 offset:2048
	ds_read_b128 v[194:197], v144 offset:3072
	ds_read_b128 v[198:201], v144 offset:4096
	ds_read_b128 v[202:205], v144 offset:5120
	ds_read_b128 v[206:209], v144 offset:6144
	ds_read_b128 v[210:213], v144 offset:7168
	global_load_lds_dwordx4 v[214:215], off
	v_lshl_add_u64 v[214:215], s[82:83], 0, v[140:141]
	s_mov_b32 m0, s31
	s_nop 0
	global_load_lds_dwordx4 v[214:215], off
	s_waitcnt vmcnt(8)
	s_waitcnt lgkmcnt(0)
	s_barrier
	s_setprio 1
	s_waitcnt lgkmcnt(0)
	v_mfma_f32_16x16x32_bf16 v[66:69], v[178:181], v[182:185], v[66:69]
	v_mfma_f32_16x16x32_bf16 v[38:41], v[170:173], v[182:185], v[38:41]
	v_mfma_f32_16x16x32_bf16 v[78:81], v[178:181], v[190:193], v[78:81]
	v_mfma_f32_16x16x32_bf16 v[46:49], v[170:173], v[190:193], v[46:49]
	v_mfma_f32_16x16x32_bf16 v[90:93], v[178:181], v[198:201], v[90:93]
	v_mfma_f32_16x16x32_bf16 v[58:61], v[170:173], v[198:201], v[58:61]
	v_mfma_f32_16x16x32_bf16 v[102:105], v[178:181], v[206:209], v[102:105]
	v_mfma_f32_16x16x32_bf16 v[70:73], v[170:173], v[206:209], v[70:73]
	v_mfma_f32_16x16x32_bf16 v[66:69], v[174:177], v[186:189], v[66:69]
	v_mfma_f32_16x16x32_bf16 v[38:41], v[166:169], v[186:189], v[38:41]
	v_mfma_f32_16x16x32_bf16 v[78:81], v[174:177], v[194:197], v[78:81]
	v_mfma_f32_16x16x32_bf16 v[46:49], v[166:169], v[194:197], v[46:49]
	v_mfma_f32_16x16x32_bf16 v[90:93], v[174:177], v[202:205], v[90:93]
	v_mfma_f32_16x16x32_bf16 v[58:61], v[166:169], v[202:205], v[58:61]
	v_mfma_f32_16x16x32_bf16 v[102:105], v[174:177], v[210:213], v[102:105]
	v_mfma_f32_16x16x32_bf16 v[70:73], v[166:169], v[210:213], v[70:73]
	s_setprio 0
	s_setprio 1
	v_mfma_f32_16x16x32_bf16 v[14:17], v[160:163], v[182:185], v[14:17]
	v_mfma_f32_16x16x32_bf16 v[2:5], v[152:155], v[182:185], v[2:5]
	v_mfma_f32_16x16x32_bf16 v[22:25], v[160:163], v[190:193], v[22:25]
	v_mfma_f32_16x16x32_bf16 v[6:9], v[152:155], v[190:193], v[6:9]
	v_mfma_f32_16x16x32_bf16 v[30:33], v[160:163], v[198:201], v[30:33]
	v_mfma_f32_16x16x32_bf16 v[10:13], v[152:155], v[198:201], v[10:13]
	v_mfma_f32_16x16x32_bf16 v[42:45], v[160:163], v[206:209], v[42:45]
	v_mfma_f32_16x16x32_bf16 v[18:21], v[152:155], v[206:209], v[18:21]
	v_mfma_f32_16x16x32_bf16 v[14:17], v[156:159], v[186:189], v[14:17]
	v_mfma_f32_16x16x32_bf16 v[2:5], v[148:151], v[186:189], v[2:5]
	v_mfma_f32_16x16x32_bf16 v[22:25], v[156:159], v[194:197], v[22:25]
	v_mfma_f32_16x16x32_bf16 v[6:9], v[148:151], v[194:197], v[6:9]
	v_mfma_f32_16x16x32_bf16 v[30:33], v[156:159], v[202:205], v[30:33]
	v_mfma_f32_16x16x32_bf16 v[10:13], v[148:151], v[202:205], v[10:13]
	v_mfma_f32_16x16x32_bf16 v[42:45], v[156:159], v[210:213], v[42:45]
	v_mfma_f32_16x16x32_bf16 v[18:21], v[148:151], v[210:213], v[18:21]
	s_setprio 0
	s_barrier
	s_mov_b32 m0, s33
	v_lshl_add_u64 v[214:215], s[14:15], 0, v[132:133]
	s_add_u32 s42, s14, 0x40000
	ds_read_b128 v[182:185], v144 offset:16384
	ds_read_b128 v[186:189], v144 offset:17408
	ds_read_b128 v[190:193], v144 offset:18432
	ds_read_b128 v[194:197], v144 offset:19456
	ds_read_b128 v[198:201], v144 offset:20480
	ds_read_b128 v[202:205], v144 offset:21504
	ds_read_b128 v[206:209], v144 offset:22528
	ds_read_b128 v[210:213], v144 offset:23552
	v_lshl_add_u64 v[216:217], s[14:15], 0, v[136:137]
	s_mov_b32 m0, s34
	s_addc_u32 s43, s15, 0
	v_lshl_add_u64 v[218:219], s[42:43], 0, v[132:133]
	s_mov_b32 m0, s35
	s_nop 0
	v_lshl_add_u64 v[218:219], s[42:43], 0, v[136:137]
	s_mov_b32 m0, s36
	s_nop 0
	v_lshl_add_u64 v[218:219], s[16:17], 0, v[130:131]
	s_mov_b32 m0, s7
	s_nop 0
	v_lshl_add_u64 v[218:219], s[16:17], 0, v[134:135]
	s_mov_b32 m0, s20
	s_nop 0
	s_waitcnt vmcnt(2)
	s_waitcnt lgkmcnt(0)
	s_barrier
	s_setprio 1
	s_waitcnt lgkmcnt(0)
	v_mfma_f32_16x16x32_bf16 v[106:109], v[178:181], v[182:185], v[106:109]
	v_mfma_f32_16x16x32_bf16 v[82:85], v[170:173], v[182:185], v[82:85]
	v_mfma_f32_16x16x32_bf16 v[118:121], v[178:181], v[190:193], v[118:121]
	v_mfma_f32_16x16x32_bf16 v[94:97], v[170:173], v[190:193], v[94:97]
	v_mfma_f32_16x16x32_bf16 v[126:129], v[178:181], v[198:201], v[126:129]
	v_mfma_f32_16x16x32_bf16 v[110:113], v[170:173], v[198:201], v[110:113]
	v_mfma_f32_16x16x32_bf16 v[122:125], v[178:181], v[206:209], v[122:125]
	v_mfma_f32_16x16x32_bf16 v[114:117], v[170:173], v[206:209], v[114:117]
	v_mfma_f32_16x16x32_bf16 v[106:109], v[174:177], v[186:189], v[106:109]
	v_mfma_f32_16x16x32_bf16 v[82:85], v[166:169], v[186:189], v[82:85]
	v_mfma_f32_16x16x32_bf16 v[118:121], v[174:177], v[194:197], v[118:121]
	v_mfma_f32_16x16x32_bf16 v[94:97], v[166:169], v[194:197], v[94:97]
	v_mfma_f32_16x16x32_bf16 v[126:129], v[174:177], v[202:205], v[126:129]
	v_mfma_f32_16x16x32_bf16 v[110:113], v[166:169], v[202:205], v[110:113]
	v_mfma_f32_16x16x32_bf16 v[122:125], v[174:177], v[210:213], v[122:125]
	v_mfma_f32_16x16x32_bf16 v[114:117], v[166:169], v[210:213], v[114:117]
	s_setprio 0
	s_setprio 1
	v_mfma_f32_16x16x32_bf16 v[50:53], v[160:163], v[182:185], v[50:53]
	v_mfma_f32_16x16x32_bf16 v[26:29], v[152:155], v[182:185], v[26:29]
	v_mfma_f32_16x16x32_bf16 v[62:65], v[160:163], v[190:193], v[62:65]
	v_mfma_f32_16x16x32_bf16 v[34:37], v[152:155], v[190:193], v[34:37]
	v_mfma_f32_16x16x32_bf16 v[86:89], v[160:163], v[198:201], v[86:89]
	v_mfma_f32_16x16x32_bf16 v[54:57], v[152:155], v[198:201], v[54:57]
	v_mfma_f32_16x16x32_bf16 v[98:101], v[160:163], v[206:209], v[98:101]
	v_mfma_f32_16x16x32_bf16 v[74:77], v[152:155], v[206:209], v[74:77]
	v_mfma_f32_16x16x32_bf16 v[50:53], v[156:159], v[186:189], v[50:53]
	v_mfma_f32_16x16x32_bf16 v[26:29], v[148:151], v[186:189], v[26:29]
	v_mfma_f32_16x16x32_bf16 v[62:65], v[156:159], v[194:197], v[62:65]
	v_mfma_f32_16x16x32_bf16 v[34:37], v[148:151], v[194:197], v[34:37]
	v_mfma_f32_16x16x32_bf16 v[86:89], v[156:159], v[202:205], v[86:89]
	v_mfma_f32_16x16x32_bf16 v[54:57], v[148:151], v[202:205], v[54:57]
	v_mfma_f32_16x16x32_bf16 v[98:101], v[156:159], v[210:213], v[98:101]
	v_mfma_f32_16x16x32_bf16 v[74:77], v[148:151], v[210:213], v[74:77]
	s_setprio 0
	s_barrier
	ds_read_b128 v[148:151], v145
	ds_read_b128 v[152:155], v145 offset:1024
	ds_read_b128 v[156:159], v145 offset:2048
	ds_read_b128 v[160:163], v145 offset:3072
	ds_read_b128 v[166:169], v146
	ds_read_b128 v[170:173], v146 offset:1024
	ds_read_b128 v[174:177], v146 offset:2048
	ds_read_b128 v[178:181], v146 offset:3072
	s_add_u32 s16, s16, 0x4000
	s_addc_u32 s17, s17, 0
	s_mov_b32 m0, s21
	v_lshl_add_u64 v[218:219], s[16:17], 0, v[130:131]
	ds_read_b128 v[182:185], v144 offset:32768
	ds_read_b128 v[186:189], v144 offset:33792
	ds_read_b128 v[190:193], v144 offset:34816
	ds_read_b128 v[194:197], v144 offset:35840
	ds_read_b128 v[198:201], v144 offset:36864
	ds_read_b128 v[202:205], v144 offset:37888
	ds_read_b128 v[206:209], v144 offset:38912
	ds_read_b128 v[210:213], v144 offset:39936
	v_lshl_add_u64 v[218:219], s[16:17], 0, v[134:135]
	s_mov_b32 m0, s22
	s_nop 0
	s_waitcnt vmcnt(0)
	s_waitcnt lgkmcnt(0)
	s_barrier
	s_setprio 1
	s_waitcnt lgkmcnt(0)
	v_mfma_f32_16x16x32_bf16 v[66:69], v[148:151], v[182:185], v[66:69]
	v_mfma_f32_16x16x32_bf16 v[38:41], v[156:159], v[182:185], v[38:41]
	v_mfma_f32_16x16x32_bf16 v[78:81], v[148:151], v[190:193], v[78:81]
	v_mfma_f32_16x16x32_bf16 v[46:49], v[156:159], v[190:193], v[46:49]
	v_mfma_f32_16x16x32_bf16 v[90:93], v[148:151], v[198:201], v[90:93]
	v_mfma_f32_16x16x32_bf16 v[58:61], v[156:159], v[198:201], v[58:61]
	v_mfma_f32_16x16x32_bf16 v[102:105], v[148:151], v[206:209], v[102:105]
	v_mfma_f32_16x16x32_bf16 v[70:73], v[156:159], v[206:209], v[70:73]
	v_mfma_f32_16x16x32_bf16 v[66:69], v[152:155], v[186:189], v[66:69]
	v_mfma_f32_16x16x32_bf16 v[38:41], v[160:163], v[186:189], v[38:41]
	v_mfma_f32_16x16x32_bf16 v[78:81], v[152:155], v[194:197], v[78:81]
	v_mfma_f32_16x16x32_bf16 v[46:49], v[160:163], v[194:197], v[46:49]
	v_mfma_f32_16x16x32_bf16 v[90:93], v[152:155], v[202:205], v[90:93]
	v_mfma_f32_16x16x32_bf16 v[58:61], v[160:163], v[202:205], v[58:61]
	v_mfma_f32_16x16x32_bf16 v[102:105], v[152:155], v[210:213], v[102:105]
	v_mfma_f32_16x16x32_bf16 v[70:73], v[160:163], v[210:213], v[70:73]
	s_setprio 0
	s_setprio 1
	v_mfma_f32_16x16x32_bf16 v[14:17], v[166:169], v[182:185], v[14:17]
	v_mfma_f32_16x16x32_bf16 v[2:5], v[174:177], v[182:185], v[2:5]
	v_mfma_f32_16x16x32_bf16 v[22:25], v[166:169], v[190:193], v[22:25]
	v_mfma_f32_16x16x32_bf16 v[6:9], v[174:177], v[190:193], v[6:9]
	v_mfma_f32_16x16x32_bf16 v[30:33], v[166:169], v[198:201], v[30:33]
	v_mfma_f32_16x16x32_bf16 v[10:13], v[174:177], v[198:201], v[10:13]
	v_mfma_f32_16x16x32_bf16 v[42:45], v[166:169], v[206:209], v[42:45]
	v_mfma_f32_16x16x32_bf16 v[18:21], v[174:177], v[206:209], v[18:21]
	v_mfma_f32_16x16x32_bf16 v[14:17], v[170:173], v[186:189], v[14:17]
	v_mfma_f32_16x16x32_bf16 v[2:5], v[178:181], v[186:189], v[2:5]
	v_mfma_f32_16x16x32_bf16 v[22:25], v[170:173], v[194:197], v[22:25]
	v_mfma_f32_16x16x32_bf16 v[6:9], v[178:181], v[194:197], v[6:9]
	v_mfma_f32_16x16x32_bf16 v[30:33], v[170:173], v[202:205], v[30:33]
	v_mfma_f32_16x16x32_bf16 v[10:13], v[178:181], v[202:205], v[10:13]
	v_mfma_f32_16x16x32_bf16 v[42:45], v[170:173], v[210:213], v[42:45]
	v_mfma_f32_16x16x32_bf16 v[18:21], v[178:181], v[210:213], v[18:21]
	s_setprio 0
	s_barrier
	s_mov_b32 m0, s37
	v_lshl_add_u64 v[214:215], v[214:215], 0, s[4:5]
	s_add_u32 s14, s14, 0x40080
	ds_read_b128 v[182:185], v144 offset:49152
	ds_read_b128 v[186:189], v144 offset:50176
	ds_read_b128 v[190:193], v144 offset:51200
	ds_read_b128 v[194:197], v144 offset:52224
	ds_read_b128 v[198:201], v144 offset:53248
	ds_read_b128 v[202:205], v144 offset:54272
	ds_read_b128 v[206:209], v144 offset:55296
	ds_read_b128 v[210:213], v144 offset:56320
	v_lshl_add_u64 v[214:215], v[216:217], 0, s[4:5]
	s_mov_b32 m0, s38
	s_addc_u32 s15, s15, 0
	v_lshl_add_u64 v[214:215], s[14:15], 0, v[132:133]
	s_mov_b32 m0, s39
	s_nop 0
	v_lshl_add_u64 v[214:215], s[14:15], 0, v[136:137]
	s_mov_b32 m0, s40
	s_nop 0
	v_lshl_add_u64 v[214:215], s[12:13], 0, v[130:131]
	s_mov_b32 m0, s23
	s_nop 0
	v_lshl_add_u64 v[214:215], s[12:13], 0, v[134:135]
	s_mov_b32 m0, s24
	s_nop 0
	s_waitcnt vmcnt(0)
	s_waitcnt lgkmcnt(0)
	s_barrier
	s_setprio 1
	s_waitcnt lgkmcnt(0)
	v_mfma_f32_16x16x32_bf16 v[106:109], v[148:151], v[182:185], v[106:109]
	v_mfma_f32_16x16x32_bf16 v[82:85], v[156:159], v[182:185], v[82:85]
	v_mfma_f32_16x16x32_bf16 v[118:121], v[148:151], v[190:193], v[118:121]
	v_mfma_f32_16x16x32_bf16 v[94:97], v[156:159], v[190:193], v[94:97]
	v_mfma_f32_16x16x32_bf16 v[126:129], v[148:151], v[198:201], v[126:129]
	v_mfma_f32_16x16x32_bf16 v[110:113], v[156:159], v[198:201], v[110:113]
	v_mfma_f32_16x16x32_bf16 v[122:125], v[148:151], v[206:209], v[122:125]
	v_mfma_f32_16x16x32_bf16 v[114:117], v[156:159], v[206:209], v[114:117]
	v_mfma_f32_16x16x32_bf16 v[106:109], v[152:155], v[186:189], v[106:109]
	v_mfma_f32_16x16x32_bf16 v[82:85], v[160:163], v[186:189], v[82:85]
	v_mfma_f32_16x16x32_bf16 v[118:121], v[152:155], v[194:197], v[118:121]
	v_mfma_f32_16x16x32_bf16 v[94:97], v[160:163], v[194:197], v[94:97]
	v_mfma_f32_16x16x32_bf16 v[126:129], v[152:155], v[202:205], v[126:129]
	v_mfma_f32_16x16x32_bf16 v[110:113], v[160:163], v[202:205], v[110:113]
	v_mfma_f32_16x16x32_bf16 v[122:125], v[152:155], v[210:213], v[122:125]
	v_mfma_f32_16x16x32_bf16 v[114:117], v[160:163], v[210:213], v[114:117]
	s_setprio 0
	s_setprio 1
	v_mfma_f32_16x16x32_bf16 v[50:53], v[166:169], v[182:185], v[50:53]
	v_mfma_f32_16x16x32_bf16 v[26:29], v[174:177], v[182:185], v[26:29]
	v_mfma_f32_16x16x32_bf16 v[62:65], v[166:169], v[190:193], v[62:65]
	v_mfma_f32_16x16x32_bf16 v[34:37], v[174:177], v[190:193], v[34:37]
	v_mfma_f32_16x16x32_bf16 v[86:89], v[166:169], v[198:201], v[86:89]
	v_mfma_f32_16x16x32_bf16 v[54:57], v[174:177], v[198:201], v[54:57]
	v_mfma_f32_16x16x32_bf16 v[98:101], v[166:169], v[206:209], v[98:101]
	v_mfma_f32_16x16x32_bf16 v[74:77], v[174:177], v[206:209], v[74:77]
	v_mfma_f32_16x16x32_bf16 v[50:53], v[170:173], v[186:189], v[50:53]
	v_mfma_f32_16x16x32_bf16 v[26:29], v[178:181], v[186:189], v[26:29]
	v_mfma_f32_16x16x32_bf16 v[62:65], v[170:173], v[194:197], v[62:65]
	v_mfma_f32_16x16x32_bf16 v[34:37], v[178:181], v[194:197], v[34:37]
	v_mfma_f32_16x16x32_bf16 v[86:89], v[170:173], v[202:205], v[86:89]
	v_mfma_f32_16x16x32_bf16 v[54:57], v[178:181], v[202:205], v[54:57]
	v_mfma_f32_16x16x32_bf16 v[98:101], v[170:173], v[210:213], v[98:101]
	v_mfma_f32_16x16x32_bf16 v[74:77], v[178:181], v[210:213], v[74:77]
	s_setprio 0
	s_barrier
	s_add_i32 s29, s29, 2
	s_add_u32 s25, s25, 0x100
	s_addc_u32 s26, s26, 0
	s_add_u32 s27, s27, 0x400000
	s_addc_u32 s28, s28, 0
	v_lshl_add_u64 v[138:139], v[138:139], 0, s[10:11]
	s_cmp_lt_u32 s29, 14
	v_lshl_add_u64 v[140:141], v[140:141], 0, s[10:11]
	s_waitcnt vmcnt(0)
	s_cmpk_gt_u32 s19, 0xff
	s_cbranch_scc1 .LBB0_923
	s_barrier
